# P3 load balance (guarded on grid==256): v^T GEMM tiles on workgroups 128-255, two each; workgroups 0-127 keep their two q tiles
# baseline (speedup 1.0000x reference)
; #define PH(n) if constexpr ((PHASE_MASK >> (n)) & 1)
; __device__ __forceinline__ bool tile_order(long L, int nM, int nN, int& pm, int& pn) {
;     const int nwg = nM * nN; if (L >= nwg) return false;
;     int wgid = (int)L; { const int q = nwg / NXCD, r = nwg % NXCD, xcd = wgid % NXCD, off = wgid / NXCD; wgid = (xcd < r ? xcd * (q + 1) : r * (q + 1) + (xcd - r) * q) + off; }
;     const int nig = WGM * nN, gid = wgid / nig, fm = gid * WGM, gsz = (nM - fm) < WGM ? (nM - fm) : WGM;
;     pm = fm + ((wgid % nig) % gsz); pn = (wgid % nig) / gsz; return true;
; __global__ void __launch_bounds__(512, 2) fwd_mega(Args a) {
;     ...
;         PH(10) {
;             pg8::Gemm g{Wv_t, CKVN, 128, 128, 128}; pg8::SchedPlain S{2, TOK / 256, G, bx, (size_t)256 * 128 * 2, (size_t)256 * 128 * 2};
;             pg8::Epi8<FVt> E{FVt{Vt}};
;             pg8::gemm_phase(lds, g, S, E, wave);
;         }
.LBB0_780:
	v_mov_b32_e32 v8, v184
	s_and_b64 vcc, exec, s[4:5]
	s_cbranch_vccnz .LBB0_805
	s_mov_b32 s99, 0
	s_cmpk_lg_u32 s18, 0x100
	s_cbranch_scc1 .Lvt_norebal
	s_cmpk_lt_i32 s2, 0x80
	s_cbranch_scc1 .LBB0_805
	s_addk_i32 s2, 0xff80
	s_movk_i32 s18, 0x80
	s_mov_b32 s99, 1
.Lvt_norebal:
	s_ashr_i32 s24, s2, 31
	s_lshr_b32 s6, s24, 29
	s_add_i32 s9, s2, s6
	s_and_b32 s6, s9, -8
	s_sub_i32 s10, s2, s6
	s_cmp_gt_i32 s10, -1
	s_cbranch_scc0 .LBB0_783
	s_lshl_b32 s8, s10, 5
	s_cbranch_execz .LBB0_784
	s_branch .LBB0_785

; #define PG8_WAIT_V(n) asm volatile("s_waitcnt vmcnt(" #n ")" ::: "memory")
; #define PG8_BAR __builtin_amdgcn_s_barrier()
; template <class Epi, class Sched>
; __device__ __forceinline__ void gemm_phase(LAS unsigned char* lds, const Gemm g, const Sched& S, const Epi& E, const int wave_) {
;     ...
;     PG8_WAIT_V(0);
;     PG8_BAR;
.LBB0_804:
	s_cmp_eq_u32 s99, 0
	s_cbranch_scc1 .Lvt_norest
	s_addk_i32 s2, 0x80
	s_movk_i32 s18, 0x100
